# GEMM k-loop LDS-DMA addressing: SGPR base + 32-bit VGPR offset (and offset:128 with M0-128) instead of 16 64-bit VALU address adds per iteration
# speedup vs baseline: 1.0047x; 1.0033x over previous
; #define PG8_STAGE(bufoff, gbase, voff) do { _Pragma("unroll") for (int _i = 0; _i < 2; ++_i) \
;         __builtin_amdgcn_global_load_lds((const unsigned*)((const char*)(gbase) + (voff)[_i]), (LAS unsigned*)(lds + (bufoff) + ldsw + _i * 8192), 16, 0, 0); } while (0)
; #define PG8_LDA(dst, b, h) do { _Pragma("unroll") for (int m = 0; m < 4; ++m) _Pragma("unroll") for (int k = 0; k < 2; ++k) dst[m][k] = *(const LAS bf16x8*)(lds + PG8_SA(b, h) + aoff + m * 2048 + k * 1024); } while (0)
; #define PG8_LDB(dst, b, h) do { _Pragma("unroll") for (int n = 0; n < 2; ++n) _Pragma("unroll") for (int k = 0; k < 2; ++k) dst[n][k] = *(const LAS bf16x8*)(lds + PG8_SB(b, h) + boff + n * 2048 + k * 1024); } while (0)
; #define PG8_MMA(ai, bj, At, Bt) do { __builtin_amdgcn_s_setprio(1); _Pragma("unroll") for (int m = 0; m < 4; ++m) _Pragma("unroll") for (int n = 0; n < 2; ++n) _Pragma("unroll") for (int k = 0; k < 2; ++k) \
;         acc[ai][bj][m][n] = __builtin_amdgcn_mfma_f32_16x16x32_bf16(Bt[n][k], At[m][k], acc[ai][bj][m][n], 0, 0, 0); __builtin_amdgcn_s_setprio(0); } while (0)
; #define PG8_WAIT_V(n) asm volatile("s_waitcnt vmcnt(" #n ")" ::: "memory")
; template <class Epi>
; __device__ __forceinline__ void gemm_phase(LAS unsigned char* lds, const Gemm g, const StaticOrder& S, const Epi& E) {
;     ...
;         const bool has_next = S.next(ui + 1, nxt);
;         const char* nA = has_next ? (const char*)g.A + (size_t)nxt.pm * tstep : cA; const char* nB = has_next ? (const char*)g.Bt + (size_t)nxt.pn * tstep : cB;
;         for (int t = 0; t < nt; t += 2) {
;             const bool last = (t == nt - 2);
;             const char* a1 = cA + (size_t)(t + 1) * kstep;
;             const char* a2 = last ? nA : cA + (size_t)(t + 2) * kstep; const char* b2 = last ? nB : cB + (size_t)(t + 2) * kstep;
;             const char* a3 = a2 + kstep; const char* b3 = b2 + kstep;
;             PG8_LDB(B0, 0, 0); PG8_LDB(B1, 0, 1); PG8_SCHED; PG8_LDA(At, 0, 0); PG8_STAGE(PG8_SA(1, 1), a1 + hstep, voffA);
;             PG8_WAIT_V(8); PG8_WAIT_L(0); PG8_BAR; PG8_MMA(0, 0, At, B0); PG8_MMA(0, 1, At, B1); PG8_BAR; PG8_SCHED;
;             PG8_LDA(At, 0, 1); PG8_STAGE(PG8_SB(0, 0), b2, voffB); PG8_STAGE(PG8_SB(0, 1), b2 + hstep, voffB); PG8_STAGE(PG8_SA(0, 0), a2, voffA);
;             PG8_WAIT_V(8); PG8_WAIT_L(0); PG8_BAR; PG8_MMA(1, 0, At, B0); PG8_MMA(1, 1, At, B1); PG8_BAR; PG8_SCHED;
.LBB0_221:
	s_add_u32 s0, s6, 0x80
	s_addc_u32 s1, s7, 0
	s_add_u32 s6, s4, 0x100
	s_addc_u32 s7, s5, 0
	s_mov_b32 s4, 0
	s_waitcnt vmcnt(0)
	s_add_i32 s71, s4, 2
	s_add_u32 s72, s0, 0x80
	s_addc_u32 s5, s1, 0
	s_cmp_eq_u32 s62, s4
	s_cselect_b32 s5, s49, s5
	s_cselect_b32 s4, s48, s72
	s_cselect_b32 s73, s51, s7
	s_cselect_b32 s72, s50, s6
	s_add_u32 s74, s72, s2
	s_addc_u32 s75, s73, 0
	s_add_u32 vcc_lo, s4, s2
	s_addc_u32 vcc_hi, s5, 0
	v_add_u32_e32 v140, 0x10000, v245
	v_add_u32_e32 v156, 0x14000, v245
	ds_read_b128 v[128:131], v140
	ds_read_b128 v[132:135], v140 offset:1024
	ds_read_b128 v[136:139], v140 offset:2048
	ds_read_b128 v[140:143], v140 offset:3072
	ds_read_b128 v[144:147], v156
	ds_read_b128 v[148:151], v156 offset:1024
	ds_read_b128 v[152:155], v156 offset:2048
	ds_read_b128 v[156:159], v156 offset:3072
	ds_read_b128 v[160:163], v247
	ds_read_b128 v[164:167], v247 offset:1024
	ds_read_b128 v[168:171], v247 offset:2048
	ds_read_b128 v[172:175], v247 offset:3072
	ds_read_b128 v[176:179], v247 offset:4096
	ds_read_b128 v[180:183], v247 offset:5120
	ds_read_b128 v[184:187], v247 offset:6144
	ds_read_b128 v[188:191], v247 offset:7168
	s_add_i32 m0, s55, 0xc000
	s_nop 0
	global_load_lds_dwordx4 v208, s[0:1]
	s_add_i32 m0, s55, 0xe000
	s_nop 0
	global_load_lds_dwordx4 v210, s[0:1]
	s_waitcnt vmcnt(8)
	s_waitcnt lgkmcnt(0)
	s_barrier
	s_setprio 1
	s_waitcnt lgkmcnt(0)
	v_mfma_f32_16x16x32_bf16 v[124:127], v[128:131], v[160:163], 0
	v_mfma_f32_16x16x32_bf16 v[120:123], v[136:139], v[160:163], 0
	v_mfma_f32_16x16x32_bf16 v[108:111], v[128:131], v[168:171], 0
	v_mfma_f32_16x16x32_bf16 v[104:107], v[136:139], v[168:171], 0
	v_mfma_f32_16x16x32_bf16 v[92:95], v[128:131], v[176:179], 0
	v_mfma_f32_16x16x32_bf16 v[88:91], v[136:139], v[176:179], 0
	v_mfma_f32_16x16x32_bf16 v[76:79], v[128:131], v[184:187], 0
	v_mfma_f32_16x16x32_bf16 v[72:75], v[136:139], v[184:187], 0
	v_mfma_f32_16x16x32_bf16 v[124:127], v[132:135], v[164:167], v[124:127]
	v_mfma_f32_16x16x32_bf16 v[120:123], v[140:143], v[164:167], v[120:123]
	v_mfma_f32_16x16x32_bf16 v[108:111], v[132:135], v[172:175], v[108:111]
	v_mfma_f32_16x16x32_bf16 v[104:107], v[140:143], v[172:175], v[104:107]
	v_mfma_f32_16x16x32_bf16 v[92:95], v[132:135], v[180:183], v[92:95]
	v_mfma_f32_16x16x32_bf16 v[88:91], v[140:143], v[180:183], v[88:91]
	v_mfma_f32_16x16x32_bf16 v[76:79], v[132:135], v[188:191], v[76:79]
	v_mfma_f32_16x16x32_bf16 v[72:75], v[140:143], v[188:191], v[72:75]
	s_setprio 0
	s_setprio 1
	v_mfma_f32_16x16x32_bf16 v[116:119], v[144:147], v[160:163], 0
	v_mfma_f32_16x16x32_bf16 v[112:115], v[152:155], v[160:163], 0
	v_mfma_f32_16x16x32_bf16 v[100:103], v[144:147], v[168:171], 0
	v_mfma_f32_16x16x32_bf16 v[96:99], v[152:155], v[168:171], 0
	v_mfma_f32_16x16x32_bf16 v[84:87], v[144:147], v[176:179], 0
	v_mfma_f32_16x16x32_bf16 v[80:83], v[152:155], v[176:179], 0
	v_mfma_f32_16x16x32_bf16 v[68:71], v[144:147], v[184:187], 0
	v_mfma_f32_16x16x32_bf16 v[64:67], v[152:155], v[184:187], 0
	v_mfma_f32_16x16x32_bf16 v[116:119], v[148:151], v[164:167], v[116:119]
	v_mfma_f32_16x16x32_bf16 v[112:115], v[156:159], v[164:167], v[112:115]
	v_mfma_f32_16x16x32_bf16 v[100:103], v[148:151], v[172:175], v[100:103]
	v_mfma_f32_16x16x32_bf16 v[96:99], v[156:159], v[172:175], v[96:99]
	v_mfma_f32_16x16x32_bf16 v[84:87], v[148:151], v[180:183], v[84:87]
	v_mfma_f32_16x16x32_bf16 v[80:83], v[156:159], v[180:183], v[80:83]
	v_mfma_f32_16x16x32_bf16 v[68:71], v[148:151], v[188:191], v[68:71]
	v_mfma_f32_16x16x32_bf16 v[64:67], v[156:159], v[188:191], v[64:67]
	s_setprio 0
	s_barrier
	ds_read_b128 v[160:163], v247 offset:16384
	ds_read_b128 v[164:167], v247 offset:17408
	ds_read_b128 v[168:171], v247 offset:18432
	ds_read_b128 v[172:175], v247 offset:19456
	ds_read_b128 v[176:179], v247 offset:20480
	ds_read_b128 v[180:183], v247 offset:21504
	ds_read_b128 v[184:187], v247 offset:22528
	ds_read_b128 v[188:191], v247 offset:23552
	s_add_i32 m0, s54, 0x10000
	s_nop 0
	global_load_lds_dwordx4 v192, s[72:73]
	s_add_i32 m0, s54, 0x12000
	s_nop 0
	global_load_lds_dwordx4 v204, s[72:73]
	s_add_i32 m0, s54, 0x14000
	s_nop 0
	global_load_lds_dwordx4 v192, s[74:75]
	s_add_i32 m0, s54, 0x16000
	s_nop 0
	global_load_lds_dwordx4 v204, s[74:75]
	s_mov_b32 m0, s55
	s_nop 0
	global_load_lds_dwordx4 v200, s[4:5]
	s_mov_b32 m0, s56
	s_nop 0
	global_load_lds_dwordx4 v202, s[4:5]
	s_waitcnt vmcnt(8)
	s_waitcnt lgkmcnt(0)
	s_barrier
	s_setprio 1
	s_waitcnt lgkmcnt(0)
	v_mfma_f32_16x16x32_bf16 v[60:63], v[128:131], v[160:163], 0
	v_mfma_f32_16x16x32_bf16 v[56:59], v[136:139], v[160:163], 0
	v_mfma_f32_16x16x32_bf16 v[44:47], v[128:131], v[168:171], 0
	v_mfma_f32_16x16x32_bf16 v[40:43], v[136:139], v[168:171], 0
	v_mfma_f32_16x16x32_bf16 v[28:31], v[128:131], v[176:179], 0
	v_mfma_f32_16x16x32_bf16 v[24:27], v[136:139], v[176:179], 0
	v_mfma_f32_16x16x32_bf16 v[12:15], v[128:131], v[184:187], 0
	v_mfma_f32_16x16x32_bf16 v[8:11], v[136:139], v[184:187], 0
	v_mfma_f32_16x16x32_bf16 v[60:63], v[132:135], v[164:167], v[60:63]
	v_mfma_f32_16x16x32_bf16 v[56:59], v[140:143], v[164:167], v[56:59]
	v_mfma_f32_16x16x32_bf16 v[44:47], v[132:135], v[172:175], v[44:47]
	v_mfma_f32_16x16x32_bf16 v[40:43], v[140:143], v[172:175], v[40:43]
	v_mfma_f32_16x16x32_bf16 v[28:31], v[132:135], v[180:183], v[28:31]
	v_mfma_f32_16x16x32_bf16 v[24:27], v[140:143], v[180:183], v[24:27]
	v_mfma_f32_16x16x32_bf16 v[12:15], v[132:135], v[188:191], v[12:15]
	v_mfma_f32_16x16x32_bf16 v[8:11], v[140:143], v[188:191], v[8:11]
	s_setprio 0
	s_setprio 1
	v_mfma_f32_16x16x32_bf16 v[52:55], v[144:147], v[160:163], 0
	v_mfma_f32_16x16x32_bf16 v[48:51], v[152:155], v[160:163], 0
	v_mfma_f32_16x16x32_bf16 v[36:39], v[144:147], v[168:171], 0
	v_mfma_f32_16x16x32_bf16 v[32:35], v[152:155], v[168:171], 0
	v_mfma_f32_16x16x32_bf16 v[20:23], v[144:147], v[176:179], 0
	v_mfma_f32_16x16x32_bf16 v[16:19], v[152:155], v[176:179], 0
	v_mfma_f32_16x16x32_bf16 v[4:7], v[144:147], v[184:187], 0
	v_mfma_f32_16x16x32_bf16 v[0:3], v[152:155], v[184:187], 0
	v_mfma_f32_16x16x32_bf16 v[52:55], v[148:151], v[164:167], v[52:55]
	v_mfma_f32_16x16x32_bf16 v[48:51], v[156:159], v[164:167], v[48:51]
	v_mfma_f32_16x16x32_bf16 v[36:39], v[148:151], v[172:175], v[36:39]
	v_mfma_f32_16x16x32_bf16 v[32:35], v[156:159], v[172:175], v[32:35]
	v_mfma_f32_16x16x32_bf16 v[20:23], v[148:151], v[180:183], v[20:23]
	v_mfma_f32_16x16x32_bf16 v[16:19], v[156:159], v[180:183], v[16:19]
	v_mfma_f32_16x16x32_bf16 v[4:7], v[148:151], v[188:191], v[4:7]
	v_mfma_f32_16x16x32_bf16 v[0:3], v[156:159], v[188:191], v[0:3]
	s_setprio 0
	s_barrier
; #define PG8_STAGE(bufoff, gbase, voff) do { _Pragma("unroll") for (int _i = 0; _i < 2; ++_i) \
;         __builtin_amdgcn_global_load_lds((const unsigned*)((const char*)(gbase) + (voff)[_i]), (LAS unsigned*)(lds + (bufoff) + ldsw + _i * 8192), 16, 0, 0); } while (0)
; #define PG8_LDA(dst, b, h) do { _Pragma("unroll") for (int m = 0; m < 4; ++m) _Pragma("unroll") for (int k = 0; k < 2; ++k) dst[m][k] = *(const LAS bf16x8*)(lds + PG8_SA(b, h) + aoff + m * 2048 + k * 1024); } while (0)
; #define PG8_LDB(dst, b, h) do { _Pragma("unroll") for (int n = 0; n < 2; ++n) _Pragma("unroll") for (int k = 0; k < 2; ++k) dst[n][k] = *(const LAS bf16x8*)(lds + PG8_SB(b, h) + boff + n * 2048 + k * 1024); } while (0)
; #define PG8_MMA(ai, bj, At, Bt) do { __builtin_amdgcn_s_setprio(1); _Pragma("unroll") for (int m = 0; m < 4; ++m) _Pragma("unroll") for (int n = 0; n < 2; ++n) _Pragma("unroll") for (int k = 0; k < 2; ++k) \
;         acc[ai][bj][m][n] = __builtin_amdgcn_mfma_f32_16x16x32_bf16(Bt[n][k], At[m][k], acc[ai][bj][m][n], 0, 0, 0); __builtin_amdgcn_s_setprio(0); } while (0)
; #define PG8_WAIT_V(n) asm volatile("s_waitcnt vmcnt(" #n ")" ::: "memory")
; #define PG8_WAIT_L(n) asm volatile("s_waitcnt lgkmcnt(" #n ")" ::: "memory")
; #define PG8_BAR __builtin_amdgcn_s_barrier()
; #define PG8_SCHED __builtin_amdgcn_sched_barrier(0)
; template <class Epi>
; __device__ __forceinline__ void gemm_phase(LAS unsigned char* lds, const Gemm g, const StaticOrder& S, const Epi& E) {
;     ...
;             PG8_LDB(B0, 1, 0); PG8_LDB(B1, 1, 1); PG8_SCHED; PG8_LDA(At, 1, 0); PG8_STAGE(PG8_SA(0, 1), a2 + hstep, voffA);
;             PG8_WAIT_V(8); PG8_WAIT_L(0); PG8_BAR; PG8_MMA(0, 0, At, B0); PG8_MMA(0, 1, At, B1); PG8_BAR; PG8_SCHED;
;             PG8_LDA(At, 1, 1); PG8_STAGE(PG8_SB(1, 0), b3, voffB); PG8_STAGE(PG8_SB(1, 1), b3 + hstep, voffB); PG8_STAGE(PG8_SA(1, 0), a3, voffA);
;             PG8_WAIT_V(8); PG8_WAIT_L(0); PG8_BAR; PG8_MMA(1, 0, At, B0); PG8_MMA(1, 1, At, B1); PG8_BAR; PG8_SCHED;
	v_add_u32_e32 v140, 0x18000, v245
	v_add_u32_e32 v156, 0x1c000, v245
	ds_read_b128 v[128:131], v140
	ds_read_b128 v[132:135], v140 offset:1024
	ds_read_b128 v[136:139], v140 offset:2048
	ds_read_b128 v[140:143], v140 offset:3072
	ds_read_b128 v[144:147], v156
	ds_read_b128 v[148:151], v156 offset:1024
	ds_read_b128 v[152:155], v156 offset:2048
	ds_read_b128 v[156:159], v156 offset:3072
	ds_read_b128 v[160:163], v247 offset:32768
	ds_read_b128 v[164:167], v247 offset:33792
	ds_read_b128 v[168:171], v247 offset:34816
	ds_read_b128 v[172:175], v247 offset:35840
	ds_read_b128 v[176:179], v247 offset:36864
	ds_read_b128 v[180:183], v247 offset:37888
	ds_read_b128 v[184:187], v247 offset:38912
	ds_read_b128 v[188:191], v247 offset:39936
	s_mov_b32 m0, s57
	s_nop 0
	global_load_lds_dwordx4 v200, vcc
	s_mov_b32 m0, s58
	s_nop 0
	global_load_lds_dwordx4 v202, vcc
	s_waitcnt vmcnt(8)
	s_waitcnt lgkmcnt(0)
	s_barrier
	s_setprio 1
	s_waitcnt lgkmcnt(0)
	v_mfma_f32_16x16x32_bf16 v[124:127], v[128:131], v[160:163], v[124:127]
	v_mfma_f32_16x16x32_bf16 v[120:123], v[136:139], v[160:163], v[120:123]
	v_mfma_f32_16x16x32_bf16 v[108:111], v[128:131], v[168:171], v[108:111]
	v_mfma_f32_16x16x32_bf16 v[104:107], v[136:139], v[168:171], v[104:107]
	v_mfma_f32_16x16x32_bf16 v[92:95], v[128:131], v[176:179], v[92:95]
	v_mfma_f32_16x16x32_bf16 v[88:91], v[136:139], v[176:179], v[88:91]
	v_mfma_f32_16x16x32_bf16 v[76:79], v[128:131], v[184:187], v[76:79]
	v_mfma_f32_16x16x32_bf16 v[72:75], v[136:139], v[184:187], v[72:75]
	v_mfma_f32_16x16x32_bf16 v[124:127], v[132:135], v[164:167], v[124:127]
	v_mfma_f32_16x16x32_bf16 v[120:123], v[140:143], v[164:167], v[120:123]
	v_mfma_f32_16x16x32_bf16 v[108:111], v[132:135], v[172:175], v[108:111]
	v_mfma_f32_16x16x32_bf16 v[104:107], v[140:143], v[172:175], v[104:107]
	v_mfma_f32_16x16x32_bf16 v[92:95], v[132:135], v[180:183], v[92:95]
	v_mfma_f32_16x16x32_bf16 v[88:91], v[140:143], v[180:183], v[88:91]
	v_mfma_f32_16x16x32_bf16 v[76:79], v[132:135], v[188:191], v[76:79]
	v_mfma_f32_16x16x32_bf16 v[72:75], v[140:143], v[188:191], v[72:75]
	s_setprio 0
	s_setprio 1
	v_mfma_f32_16x16x32_bf16 v[116:119], v[144:147], v[160:163], v[116:119]
	v_mfma_f32_16x16x32_bf16 v[112:115], v[152:155], v[160:163], v[112:115]
	v_mfma_f32_16x16x32_bf16 v[100:103], v[144:147], v[168:171], v[100:103]
	v_mfma_f32_16x16x32_bf16 v[96:99], v[152:155], v[168:171], v[96:99]
	v_mfma_f32_16x16x32_bf16 v[84:87], v[144:147], v[176:179], v[84:87]
	v_mfma_f32_16x16x32_bf16 v[80:83], v[152:155], v[176:179], v[80:83]
	v_mfma_f32_16x16x32_bf16 v[68:71], v[144:147], v[184:187], v[68:71]
	v_mfma_f32_16x16x32_bf16 v[64:67], v[152:155], v[184:187], v[64:67]
	v_mfma_f32_16x16x32_bf16 v[116:119], v[148:151], v[164:167], v[116:119]
	v_mfma_f32_16x16x32_bf16 v[112:115], v[156:159], v[164:167], v[112:115]
	v_mfma_f32_16x16x32_bf16 v[100:103], v[148:151], v[172:175], v[100:103]
	v_mfma_f32_16x16x32_bf16 v[96:99], v[156:159], v[172:175], v[96:99]
	v_mfma_f32_16x16x32_bf16 v[84:87], v[148:151], v[180:183], v[84:87]
	v_mfma_f32_16x16x32_bf16 v[80:83], v[156:159], v[180:183], v[80:83]
	v_mfma_f32_16x16x32_bf16 v[68:71], v[148:151], v[188:191], v[68:71]
	v_mfma_f32_16x16x32_bf16 v[64:67], v[156:159], v[188:191], v[64:67]
	s_setprio 0
	s_barrier
	ds_read_b128 v[160:163], v247 offset:49152
	ds_read_b128 v[164:167], v247 offset:50176
	ds_read_b128 v[168:171], v247 offset:51200
	ds_read_b128 v[172:175], v247 offset:52224
	ds_read_b128 v[176:179], v247 offset:53248
	ds_read_b128 v[180:183], v247 offset:54272
	ds_read_b128 v[184:187], v247 offset:55296
	ds_read_b128 v[188:191], v247 offset:56320
	s_add_i32 m0, s54, 0x17f80
	s_nop 0
	global_load_lds_dwordx4 v192, s[72:73] offset:128
	s_add_i32 m0, s54, 0x19f80
	s_nop 0
	global_load_lds_dwordx4 v204, s[72:73] offset:128
	s_add_i32 m0, s54, 0x1bf80
	s_nop 0
	global_load_lds_dwordx4 v192, s[74:75] offset:128
	s_add_i32 m0, s54, 0x1df80
	s_nop 0
	global_load_lds_dwordx4 v204, s[74:75] offset:128
	s_add_i32 m0, s59, 0xffffff80
	s_nop 0
	global_load_lds_dwordx4 v200, s[4:5] offset:128
	s_add_i32 m0, s60, 0xffffff80
	s_nop 0
	global_load_lds_dwordx4 v202, s[4:5] offset:128
	s_waitcnt vmcnt(8)
	s_waitcnt lgkmcnt(0)
	s_barrier
	s_setprio 1
	s_waitcnt lgkmcnt(0)
	v_mfma_f32_16x16x32_bf16 v[60:63], v[128:131], v[160:163], v[60:63]
	v_mfma_f32_16x16x32_bf16 v[56:59], v[136:139], v[160:163], v[56:59]
	v_mfma_f32_16x16x32_bf16 v[44:47], v[128:131], v[168:171], v[44:47]
	v_mfma_f32_16x16x32_bf16 v[40:43], v[136:139], v[168:171], v[40:43]
	v_mfma_f32_16x16x32_bf16 v[28:31], v[128:131], v[176:179], v[28:31]
	v_mfma_f32_16x16x32_bf16 v[24:27], v[136:139], v[176:179], v[24:27]
	v_mfma_f32_16x16x32_bf16 v[12:15], v[128:131], v[184:187], v[12:15]
	v_mfma_f32_16x16x32_bf16 v[8:11], v[136:139], v[184:187], v[8:11]
	v_mfma_f32_16x16x32_bf16 v[60:63], v[132:135], v[164:167], v[60:63]
	v_mfma_f32_16x16x32_bf16 v[56:59], v[140:143], v[164:167], v[56:59]
	v_mfma_f32_16x16x32_bf16 v[44:47], v[132:135], v[172:175], v[44:47]
	v_mfma_f32_16x16x32_bf16 v[40:43], v[140:143], v[172:175], v[40:43]
	v_mfma_f32_16x16x32_bf16 v[28:31], v[132:135], v[180:183], v[28:31]
	v_mfma_f32_16x16x32_bf16 v[24:27], v[140:143], v[180:183], v[24:27]
	v_mfma_f32_16x16x32_bf16 v[12:15], v[132:135], v[188:191], v[12:15]
	v_mfma_f32_16x16x32_bf16 v[8:11], v[140:143], v[188:191], v[8:11]
	s_setprio 0
	s_setprio 1
	v_mfma_f32_16x16x32_bf16 v[52:55], v[144:147], v[160:163], v[52:55]
	v_mfma_f32_16x16x32_bf16 v[48:51], v[152:155], v[160:163], v[48:51]
	v_mfma_f32_16x16x32_bf16 v[36:39], v[144:147], v[168:171], v[36:39]
	v_mfma_f32_16x16x32_bf16 v[32:35], v[152:155], v[168:171], v[32:35]
	v_mfma_f32_16x16x32_bf16 v[20:23], v[144:147], v[176:179], v[20:23]
	v_mfma_f32_16x16x32_bf16 v[16:19], v[152:155], v[176:179], v[16:19]
	v_mfma_f32_16x16x32_bf16 v[4:7], v[144:147], v[184:187], v[4:7]
	v_mfma_f32_16x16x32_bf16 v[0:3], v[152:155], v[184:187], v[0:3]
	v_mfma_f32_16x16x32_bf16 v[52:55], v[148:151], v[164:167], v[52:55]
	v_mfma_f32_16x16x32_bf16 v[48:51], v[156:159], v[164:167], v[48:51]
	v_mfma_f32_16x16x32_bf16 v[36:39], v[148:151], v[172:175], v[36:39]
	v_mfma_f32_16x16x32_bf16 v[32:35], v[156:159], v[172:175], v[32:35]
	v_mfma_f32_16x16x32_bf16 v[20:23], v[148:151], v[180:183], v[20:23]
	v_mfma_f32_16x16x32_bf16 v[16:19], v[156:159], v[180:183], v[16:19]
	v_mfma_f32_16x16x32_bf16 v[4:7], v[148:151], v[188:191], v[4:7]
	v_mfma_f32_16x16x32_bf16 v[0:3], v[156:159], v[188:191], v[0:3]
	s_setprio 0
	s_barrier
	s_add_u32 s0, s0, 0x100
	s_addc_u32 s1, s1, 0
	s_add_u32 s6, s6, 0x100
	s_addc_u32 s7, s7, 0
	s_cmp_ge_u32 s71, s61
	s_mov_b32 s4, s71
	s_cbranch_scc1 .Lk_done
; #define PG8_STAGE(bufoff, gbase, voff) do { _Pragma("unroll") for (int _i = 0; _i < 2; ++_i) \
;         __builtin_amdgcn_global_load_lds((const unsigned*)((const char*)(gbase) + (voff)[_i]), (LAS unsigned*)(lds + (bufoff) + ldsw + _i * 8192), 16, 0, 0); } while (0)
; #define PG8_LDA(dst, b, h) do { _Pragma("unroll") for (int m = 0; m < 4; ++m) _Pragma("unroll") for (int k = 0; k < 2; ++k) dst[m][k] = *(const LAS bf16x8*)(lds + PG8_SA(b, h) + aoff + m * 2048 + k * 1024); } while (0)
; #define PG8_LDB(dst, b, h) do { _Pragma("unroll") for (int n = 0; n < 2; ++n) _Pragma("unroll") for (int k = 0; k < 2; ++k) dst[n][k] = *(const LAS bf16x8*)(lds + PG8_SB(b, h) + boff + n * 2048 + k * 1024); } while (0)
; #define PG8_MMA(ai, bj, At, Bt) do { __builtin_amdgcn_s_setprio(1); _Pragma("unroll") for (int m = 0; m < 4; ++m) _Pragma("unroll") for (int n = 0; n < 2; ++n) _Pragma("unroll") for (int k = 0; k < 2; ++k) \
;         acc[ai][bj][m][n] = __builtin_amdgcn_mfma_f32_16x16x32_bf16(Bt[n][k], At[m][k], acc[ai][bj][m][n], 0, 0, 0); __builtin_amdgcn_s_setprio(0); } while (0)
; #define PG8_WAIT_V(n) asm volatile("s_waitcnt vmcnt(" #n ")" ::: "memory")
; #define PG8_WAIT_L(n) asm volatile("s_waitcnt lgkmcnt(" #n ")" ::: "memory")
; #define PG8_BAR __builtin_amdgcn_s_barrier()
; #define PG8_SCHED __builtin_amdgcn_sched_barrier(0)
; template <class Epi>
; __device__ __forceinline__ void gemm_phase(LAS unsigned char* lds, const Gemm g, const StaticOrder& S, const Epi& E) {
;     ...
;         for (int t = 0; t < nt; t += 2) {
;             const bool last = (t == nt - 2);
;             const char* a1 = cA + (size_t)(t + 1) * kstep;
;             const char* a2 = last ? nA : cA + (size_t)(t + 2) * kstep; const char* b2 = last ? nB : cB + (size_t)(t + 2) * kstep;
;             const char* a3 = a2 + kstep; const char* b3 = b2 + kstep;
;             PG8_LDB(B0, 0, 0); PG8_LDB(B1, 0, 1); PG8_SCHED; PG8_LDA(At, 0, 0); PG8_STAGE(PG8_SA(1, 1), a1 + hstep, voffA);
;             PG8_WAIT_V(8); PG8_WAIT_L(0); PG8_BAR; PG8_MMA(0, 0, At, B0); PG8_MMA(0, 1, At, B1); PG8_BAR; PG8_SCHED;
;             PG8_LDA(At, 0, 1); PG8_STAGE(PG8_SB(0, 0), b2, voffB); PG8_STAGE(PG8_SB(0, 1), b2 + hstep, voffB); PG8_STAGE(PG8_SA(0, 0), a2, voffA);
;             PG8_WAIT_V(8); PG8_WAIT_L(0); PG8_BAR; PG8_MMA(1, 0, At, B0); PG8_MMA(1, 1, At, B1); PG8_BAR; PG8_SCHED;
.LBB0_222:
	s_add_i32 s71, s4, 2
	s_add_u32 s72, s0, 0x80
	s_addc_u32 s5, s1, 0
	s_cmp_eq_u32 s62, s4
	s_cselect_b32 s5, s49, s5
	s_cselect_b32 s4, s48, s72
	s_cselect_b32 s73, s51, s7
	s_cselect_b32 s72, s50, s6
	s_add_u32 s74, s72, s2
	s_addc_u32 s75, s73, 0
	s_add_u32 vcc_lo, s4, s2
	s_addc_u32 vcc_hi, s5, 0
	v_add_u32_e32 v140, 0x10000, v245
	v_add_u32_e32 v156, 0x14000, v245
	ds_read_b128 v[128:131], v140
	ds_read_b128 v[132:135], v140 offset:1024
	ds_read_b128 v[136:139], v140 offset:2048
	ds_read_b128 v[140:143], v140 offset:3072
	ds_read_b128 v[144:147], v156
	ds_read_b128 v[148:151], v156 offset:1024
	ds_read_b128 v[152:155], v156 offset:2048
	ds_read_b128 v[156:159], v156 offset:3072
	ds_read_b128 v[160:163], v247
	ds_read_b128 v[164:167], v247 offset:1024
	ds_read_b128 v[168:171], v247 offset:2048
	ds_read_b128 v[172:175], v247 offset:3072
	ds_read_b128 v[176:179], v247 offset:4096
	ds_read_b128 v[180:183], v247 offset:5120
	ds_read_b128 v[184:187], v247 offset:6144
	ds_read_b128 v[188:191], v247 offset:7168
	s_add_i32 m0, s55, 0xc000
	s_nop 0
	global_load_lds_dwordx4 v208, s[0:1]
	s_add_i32 m0, s55, 0xe000
	s_nop 0
	global_load_lds_dwordx4 v210, s[0:1]
	s_waitcnt vmcnt(8)
	s_waitcnt lgkmcnt(0)
	s_barrier
	s_setprio 1
	s_waitcnt lgkmcnt(0)
	v_mfma_f32_16x16x32_bf16 v[124:127], v[128:131], v[160:163], v[124:127]
	v_mfma_f32_16x16x32_bf16 v[120:123], v[136:139], v[160:163], v[120:123]
	v_mfma_f32_16x16x32_bf16 v[108:111], v[128:131], v[168:171], v[108:111]
	v_mfma_f32_16x16x32_bf16 v[104:107], v[136:139], v[168:171], v[104:107]
	v_mfma_f32_16x16x32_bf16 v[92:95], v[128:131], v[176:179], v[92:95]
	v_mfma_f32_16x16x32_bf16 v[88:91], v[136:139], v[176:179], v[88:91]
	v_mfma_f32_16x16x32_bf16 v[76:79], v[128:131], v[184:187], v[76:79]
	v_mfma_f32_16x16x32_bf16 v[72:75], v[136:139], v[184:187], v[72:75]
	v_mfma_f32_16x16x32_bf16 v[124:127], v[132:135], v[164:167], v[124:127]
	v_mfma_f32_16x16x32_bf16 v[120:123], v[140:143], v[164:167], v[120:123]
	v_mfma_f32_16x16x32_bf16 v[108:111], v[132:135], v[172:175], v[108:111]
	v_mfma_f32_16x16x32_bf16 v[104:107], v[140:143], v[172:175], v[104:107]
	v_mfma_f32_16x16x32_bf16 v[92:95], v[132:135], v[180:183], v[92:95]
	v_mfma_f32_16x16x32_bf16 v[88:91], v[140:143], v[180:183], v[88:91]
	v_mfma_f32_16x16x32_bf16 v[76:79], v[132:135], v[188:191], v[76:79]
	v_mfma_f32_16x16x32_bf16 v[72:75], v[140:143], v[188:191], v[72:75]
	s_setprio 0
	s_setprio 1
	v_mfma_f32_16x16x32_bf16 v[116:119], v[144:147], v[160:163], v[116:119]
	v_mfma_f32_16x16x32_bf16 v[112:115], v[152:155], v[160:163], v[112:115]
	v_mfma_f32_16x16x32_bf16 v[100:103], v[144:147], v[168:171], v[100:103]
	v_mfma_f32_16x16x32_bf16 v[96:99], v[152:155], v[168:171], v[96:99]
	v_mfma_f32_16x16x32_bf16 v[84:87], v[144:147], v[176:179], v[84:87]
	v_mfma_f32_16x16x32_bf16 v[80:83], v[152:155], v[176:179], v[80:83]
	v_mfma_f32_16x16x32_bf16 v[68:71], v[144:147], v[184:187], v[68:71]
	v_mfma_f32_16x16x32_bf16 v[64:67], v[152:155], v[184:187], v[64:67]
	v_mfma_f32_16x16x32_bf16 v[116:119], v[148:151], v[164:167], v[116:119]
	v_mfma_f32_16x16x32_bf16 v[112:115], v[156:159], v[164:167], v[112:115]
	v_mfma_f32_16x16x32_bf16 v[100:103], v[148:151], v[172:175], v[100:103]
	v_mfma_f32_16x16x32_bf16 v[96:99], v[156:159], v[172:175], v[96:99]
	v_mfma_f32_16x16x32_bf16 v[84:87], v[148:151], v[180:183], v[84:87]
	v_mfma_f32_16x16x32_bf16 v[80:83], v[156:159], v[180:183], v[80:83]
	v_mfma_f32_16x16x32_bf16 v[68:71], v[148:151], v[188:191], v[68:71]
	v_mfma_f32_16x16x32_bf16 v[64:67], v[156:159], v[188:191], v[64:67]
	s_setprio 0
	s_barrier
	ds_read_b128 v[160:163], v247 offset:16384
	ds_read_b128 v[164:167], v247 offset:17408
	ds_read_b128 v[168:171], v247 offset:18432
	ds_read_b128 v[172:175], v247 offset:19456
	ds_read_b128 v[176:179], v247 offset:20480
	ds_read_b128 v[180:183], v247 offset:21504
	ds_read_b128 v[184:187], v247 offset:22528
	ds_read_b128 v[188:191], v247 offset:23552
	s_add_i32 m0, s54, 0x10000
	s_nop 0
	global_load_lds_dwordx4 v192, s[72:73]
	s_add_i32 m0, s54, 0x12000
	s_nop 0
	global_load_lds_dwordx4 v204, s[72:73]
	s_add_i32 m0, s54, 0x14000
	s_nop 0
	global_load_lds_dwordx4 v192, s[74:75]
	s_add_i32 m0, s54, 0x16000
	s_nop 0
	global_load_lds_dwordx4 v204, s[74:75]
	s_mov_b32 m0, s55
	s_nop 0
	global_load_lds_dwordx4 v200, s[4:5]
	s_mov_b32 m0, s56
	s_nop 0
	global_load_lds_dwordx4 v202, s[4:5]
	s_waitcnt vmcnt(8)
	s_waitcnt lgkmcnt(0)
	s_barrier
	s_setprio 1
	s_waitcnt lgkmcnt(0)
	v_mfma_f32_16x16x32_bf16 v[60:63], v[128:131], v[160:163], v[60:63]
	v_mfma_f32_16x16x32_bf16 v[56:59], v[136:139], v[160:163], v[56:59]
	v_mfma_f32_16x16x32_bf16 v[44:47], v[128:131], v[168:171], v[44:47]
	v_mfma_f32_16x16x32_bf16 v[40:43], v[136:139], v[168:171], v[40:43]
	v_mfma_f32_16x16x32_bf16 v[28:31], v[128:131], v[176:179], v[28:31]
	v_mfma_f32_16x16x32_bf16 v[24:27], v[136:139], v[176:179], v[24:27]
	v_mfma_f32_16x16x32_bf16 v[12:15], v[128:131], v[184:187], v[12:15]
	v_mfma_f32_16x16x32_bf16 v[8:11], v[136:139], v[184:187], v[8:11]
	v_mfma_f32_16x16x32_bf16 v[60:63], v[132:135], v[164:167], v[60:63]
	v_mfma_f32_16x16x32_bf16 v[56:59], v[140:143], v[164:167], v[56:59]
	v_mfma_f32_16x16x32_bf16 v[44:47], v[132:135], v[172:175], v[44:47]
	v_mfma_f32_16x16x32_bf16 v[40:43], v[140:143], v[172:175], v[40:43]
	v_mfma_f32_16x16x32_bf16 v[28:31], v[132:135], v[180:183], v[28:31]
	v_mfma_f32_16x16x32_bf16 v[24:27], v[140:143], v[180:183], v[24:27]
	v_mfma_f32_16x16x32_bf16 v[12:15], v[132:135], v[188:191], v[12:15]
	v_mfma_f32_16x16x32_bf16 v[8:11], v[140:143], v[188:191], v[8:11]
	s_setprio 0
	s_setprio 1
	v_mfma_f32_16x16x32_bf16 v[52:55], v[144:147], v[160:163], v[52:55]
	v_mfma_f32_16x16x32_bf16 v[48:51], v[152:155], v[160:163], v[48:51]
	v_mfma_f32_16x16x32_bf16 v[36:39], v[144:147], v[168:171], v[36:39]
	v_mfma_f32_16x16x32_bf16 v[32:35], v[152:155], v[168:171], v[32:35]
	v_mfma_f32_16x16x32_bf16 v[20:23], v[144:147], v[176:179], v[20:23]
	v_mfma_f32_16x16x32_bf16 v[16:19], v[152:155], v[176:179], v[16:19]
	v_mfma_f32_16x16x32_bf16 v[4:7], v[144:147], v[184:187], v[4:7]
	v_mfma_f32_16x16x32_bf16 v[0:3], v[152:155], v[184:187], v[0:3]
	v_mfma_f32_16x16x32_bf16 v[52:55], v[148:151], v[164:167], v[52:55]
	v_mfma_f32_16x16x32_bf16 v[48:51], v[156:159], v[164:167], v[48:51]
	v_mfma_f32_16x16x32_bf16 v[36:39], v[148:151], v[172:175], v[36:39]
	v_mfma_f32_16x16x32_bf16 v[32:35], v[156:159], v[172:175], v[32:35]
	v_mfma_f32_16x16x32_bf16 v[20:23], v[148:151], v[180:183], v[20:23]
	v_mfma_f32_16x16x32_bf16 v[16:19], v[156:159], v[180:183], v[16:19]
	v_mfma_f32_16x16x32_bf16 v[4:7], v[148:151], v[188:191], v[4:7]
	v_mfma_f32_16x16x32_bf16 v[0:3], v[156:159], v[188:191], v[0:3]
	s_setprio 0
	s_barrier
; #define PG8_STAGE(bufoff, gbase, voff) do { _Pragma("unroll") for (int _i = 0; _i < 2; ++_i) \
;         __builtin_amdgcn_global_load_lds((const unsigned*)((const char*)(gbase) + (voff)[_i]), (LAS unsigned*)(lds + (bufoff) + ldsw + _i * 8192), 16, 0, 0); } while (0)
; #define PG8_LDA(dst, b, h) do { _Pragma("unroll") for (int m = 0; m < 4; ++m) _Pragma("unroll") for (int k = 0; k < 2; ++k) dst[m][k] = *(const LAS bf16x8*)(lds + PG8_SA(b, h) + aoff + m * 2048 + k * 1024); } while (0)
; #define PG8_LDB(dst, b, h) do { _Pragma("unroll") for (int n = 0; n < 2; ++n) _Pragma("unroll") for (int k = 0; k < 2; ++k) dst[n][k] = *(const LAS bf16x8*)(lds + PG8_SB(b, h) + boff + n * 2048 + k * 1024); } while (0)
; #define PG8_MMA(ai, bj, At, Bt) do { __builtin_amdgcn_s_setprio(1); _Pragma("unroll") for (int m = 0; m < 4; ++m) _Pragma("unroll") for (int n = 0; n < 2; ++n) _Pragma("unroll") for (int k = 0; k < 2; ++k) \
;         acc[ai][bj][m][n] = __builtin_amdgcn_mfma_f32_16x16x32_bf16(Bt[n][k], At[m][k], acc[ai][bj][m][n], 0, 0, 0); __builtin_amdgcn_s_setprio(0); } while (0)
; #define PG8_WAIT_V(n) asm volatile("s_waitcnt vmcnt(" #n ")" ::: "memory")
; #define PG8_WAIT_L(n) asm volatile("s_waitcnt lgkmcnt(" #n ")" ::: "memory")
; #define PG8_BAR __builtin_amdgcn_s_barrier()
; #define PG8_SCHED __builtin_amdgcn_sched_barrier(0)
; template <class Epi>
; __device__ __forceinline__ void gemm_phase(LAS unsigned char* lds, const Gemm g, const StaticOrder& S, const Epi& E) {
;     ...
;             PG8_LDB(B0, 1, 0); PG8_LDB(B1, 1, 1); PG8_SCHED; PG8_LDA(At, 1, 0); PG8_STAGE(PG8_SA(0, 1), a2 + hstep, voffA);
;             PG8_WAIT_V(8); PG8_WAIT_L(0); PG8_BAR; PG8_MMA(0, 0, At, B0); PG8_MMA(0, 1, At, B1); PG8_BAR; PG8_SCHED;
;             PG8_LDA(At, 1, 1); PG8_STAGE(PG8_SB(1, 0), b3, voffB); PG8_STAGE(PG8_SB(1, 1), b3 + hstep, voffB); PG8_STAGE(PG8_SA(1, 0), a3, voffA);
;             PG8_WAIT_V(8); PG8_WAIT_L(0); PG8_BAR; PG8_MMA(1, 0, At, B0); PG8_MMA(1, 1, At, B1); PG8_BAR; PG8_SCHED;
	v_add_u32_e32 v140, 0x18000, v245
	v_add_u32_e32 v156, 0x1c000, v245
	ds_read_b128 v[128:131], v140
	ds_read_b128 v[132:135], v140 offset:1024
	ds_read_b128 v[136:139], v140 offset:2048
	ds_read_b128 v[140:143], v140 offset:3072
	ds_read_b128 v[144:147], v156
	ds_read_b128 v[148:151], v156 offset:1024
	ds_read_b128 v[152:155], v156 offset:2048
	ds_read_b128 v[156:159], v156 offset:3072
	ds_read_b128 v[160:163], v247 offset:32768
	ds_read_b128 v[164:167], v247 offset:33792
	ds_read_b128 v[168:171], v247 offset:34816
	ds_read_b128 v[172:175], v247 offset:35840
	ds_read_b128 v[176:179], v247 offset:36864
	ds_read_b128 v[180:183], v247 offset:37888
	ds_read_b128 v[184:187], v247 offset:38912
	ds_read_b128 v[188:191], v247 offset:39936
	s_mov_b32 m0, s57
	s_nop 0
	global_load_lds_dwordx4 v200, vcc
	s_mov_b32 m0, s58
	s_nop 0
	global_load_lds_dwordx4 v202, vcc
	s_waitcnt vmcnt(8)
	s_waitcnt lgkmcnt(0)
	s_barrier
	s_setprio 1
	s_waitcnt lgkmcnt(0)
	v_mfma_f32_16x16x32_bf16 v[124:127], v[128:131], v[160:163], v[124:127]
	v_mfma_f32_16x16x32_bf16 v[120:123], v[136:139], v[160:163], v[120:123]
	v_mfma_f32_16x16x32_bf16 v[108:111], v[128:131], v[168:171], v[108:111]
	v_mfma_f32_16x16x32_bf16 v[104:107], v[136:139], v[168:171], v[104:107]
	v_mfma_f32_16x16x32_bf16 v[92:95], v[128:131], v[176:179], v[92:95]
	v_mfma_f32_16x16x32_bf16 v[88:91], v[136:139], v[176:179], v[88:91]
	v_mfma_f32_16x16x32_bf16 v[76:79], v[128:131], v[184:187], v[76:79]
	v_mfma_f32_16x16x32_bf16 v[72:75], v[136:139], v[184:187], v[72:75]
	v_mfma_f32_16x16x32_bf16 v[124:127], v[132:135], v[164:167], v[124:127]
	v_mfma_f32_16x16x32_bf16 v[120:123], v[140:143], v[164:167], v[120:123]
	v_mfma_f32_16x16x32_bf16 v[108:111], v[132:135], v[172:175], v[108:111]
	v_mfma_f32_16x16x32_bf16 v[104:107], v[140:143], v[172:175], v[104:107]
	v_mfma_f32_16x16x32_bf16 v[92:95], v[132:135], v[180:183], v[92:95]
	v_mfma_f32_16x16x32_bf16 v[88:91], v[140:143], v[180:183], v[88:91]
	v_mfma_f32_16x16x32_bf16 v[76:79], v[132:135], v[188:191], v[76:79]
	v_mfma_f32_16x16x32_bf16 v[72:75], v[140:143], v[188:191], v[72:75]
	s_setprio 0
	s_setprio 1
	v_mfma_f32_16x16x32_bf16 v[116:119], v[144:147], v[160:163], v[116:119]
	v_mfma_f32_16x16x32_bf16 v[112:115], v[152:155], v[160:163], v[112:115]
	v_mfma_f32_16x16x32_bf16 v[100:103], v[144:147], v[168:171], v[100:103]
	v_mfma_f32_16x16x32_bf16 v[96:99], v[152:155], v[168:171], v[96:99]
	v_mfma_f32_16x16x32_bf16 v[84:87], v[144:147], v[176:179], v[84:87]
	v_mfma_f32_16x16x32_bf16 v[80:83], v[152:155], v[176:179], v[80:83]
	v_mfma_f32_16x16x32_bf16 v[68:71], v[144:147], v[184:187], v[68:71]
	v_mfma_f32_16x16x32_bf16 v[64:67], v[152:155], v[184:187], v[64:67]
	v_mfma_f32_16x16x32_bf16 v[116:119], v[148:151], v[164:167], v[116:119]
	v_mfma_f32_16x16x32_bf16 v[112:115], v[156:159], v[164:167], v[112:115]
	v_mfma_f32_16x16x32_bf16 v[100:103], v[148:151], v[172:175], v[100:103]
	v_mfma_f32_16x16x32_bf16 v[96:99], v[156:159], v[172:175], v[96:99]
	v_mfma_f32_16x16x32_bf16 v[84:87], v[148:151], v[180:183], v[84:87]
	v_mfma_f32_16x16x32_bf16 v[80:83], v[156:159], v[180:183], v[80:83]
	v_mfma_f32_16x16x32_bf16 v[68:71], v[148:151], v[188:191], v[68:71]
	v_mfma_f32_16x16x32_bf16 v[64:67], v[156:159], v[188:191], v[64:67]
	s_setprio 0
	s_barrier
	ds_read_b128 v[160:163], v247 offset:49152
	ds_read_b128 v[164:167], v247 offset:50176
	ds_read_b128 v[168:171], v247 offset:51200
	ds_read_b128 v[172:175], v247 offset:52224
	ds_read_b128 v[176:179], v247 offset:53248
	ds_read_b128 v[180:183], v247 offset:54272
	ds_read_b128 v[184:187], v247 offset:55296
	ds_read_b128 v[188:191], v247 offset:56320
	s_add_i32 m0, s54, 0x17f80
	s_nop 0
	global_load_lds_dwordx4 v192, s[72:73] offset:128
	s_add_i32 m0, s54, 0x19f80
	s_nop 0
	global_load_lds_dwordx4 v204, s[72:73] offset:128
	s_add_i32 m0, s54, 0x1bf80
	s_nop 0
	global_load_lds_dwordx4 v192, s[74:75] offset:128
	s_add_i32 m0, s54, 0x1df80
	s_nop 0
	global_load_lds_dwordx4 v204, s[74:75] offset:128
	s_add_i32 m0, s59, 0xffffff80
	s_nop 0
	global_load_lds_dwordx4 v200, s[4:5] offset:128
	s_add_i32 m0, s60, 0xffffff80
	s_nop 0
	global_load_lds_dwordx4 v202, s[4:5] offset:128
	s_waitcnt vmcnt(8)
	s_waitcnt lgkmcnt(0)
	s_barrier
	s_setprio 1
	s_waitcnt lgkmcnt(0)
	v_mfma_f32_16x16x32_bf16 v[60:63], v[128:131], v[160:163], v[60:63]
	v_mfma_f32_16x16x32_bf16 v[56:59], v[136:139], v[160:163], v[56:59]
	v_mfma_f32_16x16x32_bf16 v[44:47], v[128:131], v[168:171], v[44:47]
	v_mfma_f32_16x16x32_bf16 v[40:43], v[136:139], v[168:171], v[40:43]
	v_mfma_f32_16x16x32_bf16 v[28:31], v[128:131], v[176:179], v[28:31]
	v_mfma_f32_16x16x32_bf16 v[24:27], v[136:139], v[176:179], v[24:27]
	v_mfma_f32_16x16x32_bf16 v[12:15], v[128:131], v[184:187], v[12:15]
	v_mfma_f32_16x16x32_bf16 v[8:11], v[136:139], v[184:187], v[8:11]
	v_mfma_f32_16x16x32_bf16 v[60:63], v[132:135], v[164:167], v[60:63]
	v_mfma_f32_16x16x32_bf16 v[56:59], v[140:143], v[164:167], v[56:59]
	v_mfma_f32_16x16x32_bf16 v[44:47], v[132:135], v[172:175], v[44:47]
	v_mfma_f32_16x16x32_bf16 v[40:43], v[140:143], v[172:175], v[40:43]
	v_mfma_f32_16x16x32_bf16 v[28:31], v[132:135], v[180:183], v[28:31]
	v_mfma_f32_16x16x32_bf16 v[24:27], v[140:143], v[180:183], v[24:27]
	v_mfma_f32_16x16x32_bf16 v[12:15], v[132:135], v[188:191], v[12:15]
	v_mfma_f32_16x16x32_bf16 v[8:11], v[140:143], v[188:191], v[8:11]
	s_setprio 0
	s_setprio 1
	v_mfma_f32_16x16x32_bf16 v[52:55], v[144:147], v[160:163], v[52:55]
	v_mfma_f32_16x16x32_bf16 v[48:51], v[152:155], v[160:163], v[48:51]
	v_mfma_f32_16x16x32_bf16 v[36:39], v[144:147], v[168:171], v[36:39]
	v_mfma_f32_16x16x32_bf16 v[32:35], v[152:155], v[168:171], v[32:35]
	v_mfma_f32_16x16x32_bf16 v[20:23], v[144:147], v[176:179], v[20:23]
	v_mfma_f32_16x16x32_bf16 v[16:19], v[152:155], v[176:179], v[16:19]
	v_mfma_f32_16x16x32_bf16 v[4:7], v[144:147], v[184:187], v[4:7]
	v_mfma_f32_16x16x32_bf16 v[0:3], v[152:155], v[184:187], v[0:3]
	v_mfma_f32_16x16x32_bf16 v[52:55], v[148:151], v[164:167], v[52:55]
	v_mfma_f32_16x16x32_bf16 v[48:51], v[156:159], v[164:167], v[48:51]
	v_mfma_f32_16x16x32_bf16 v[36:39], v[148:151], v[172:175], v[36:39]
	v_mfma_f32_16x16x32_bf16 v[32:35], v[156:159], v[172:175], v[32:35]
	v_mfma_f32_16x16x32_bf16 v[20:23], v[148:151], v[180:183], v[20:23]
	v_mfma_f32_16x16x32_bf16 v[16:19], v[156:159], v[180:183], v[16:19]
	v_mfma_f32_16x16x32_bf16 v[4:7], v[148:151], v[188:191], v[4:7]
	v_mfma_f32_16x16x32_bf16 v[0:3], v[156:159], v[188:191], v[0:3]
	s_setprio 0
	s_barrier
	s_add_u32 s0, s0, 0x100
	s_addc_u32 s1, s1, 0
	s_add_u32 s6, s6, 0x100
	s_addc_u32 s7, s7, 0
	s_cmp_ge_u32 s71, s61
	s_mov_b32 s4, s71
	s_cbranch_scc0 .LBB0_222
